# HGRN2 prep: the denormal-input guard of the 16 logf expansions removed (arguments are clamped to >= 1e-30, the guard is dead for every input); bit-identical
# speedup vs baseline: 1.0049x; 1.0030x over previous
; DI float frcp(float x) { return __builtin_amdgcn_rcpf(x); }
; DI void phase_prep(int l, int wv, bool last, bool dry = false) {
;     ...
;             const f32x4 lfa = *(const f32x4*)(lbt + c0), lfc = *(const f32x4*)(lbt + c0 + 4), lba = *(const f32x4*)(lbt + DC + c0), lbc = *(const f32x4*)(lbt + DC + c0 + 4);
; #pragma unroll
;             for (int i = 0; i < 8; ++i) { const float lbf = i < 4 ? lfa[i & 3] : lfc[i & 3], lbb = i < 4 ? lba[i & 3] : lbc[i & 3];
;                 const float ef = __expf(fminf(fmaxf(-zf[i], -80.f), 80.f)), eb = __expf(fminf(fmaxf(-zb[i], -80.f), 80.f)), sf = frcp(1.0f + ef), sb = frcp(1.0f + eb);
;                 lff[i] = __logf(fmaxf(lbf + (1.0f - lbf) * sf, F_MIN)); kf[i] = (1.0f - lbf) * (ef * sf);
;                 lfb[i] = __logf(fmaxf(lbb + (1.0f - lbb) * sb, F_MIN)); kb[i] = (1.0f - lbb) * (eb * sb);
;                 qs[i] = q[i] * frcp(1.0f + __expf(-q[i])) * QSCALE; }
;         }
; #pragma unroll
;         for (int d = 1; d < 8; d <<= 1) {
; #pragma unroll
;             for (int i = 0; i < 8; ++i) { const float o = __shfl_up(lff[i], 8 * d); if (pl >= d) lff[i] += o; const float o2 = __shfl_down(lfb[i], 8 * d); if (pl + d < 8) lfb[i] += o2; } }
.Lprep_pf_skip_A:
	v_lshlrev_b32_e32 v98, 16, v44
	v_max_f32_e64 v98, -v98, -v98
	s_mov_b32 s29, 0xc2a00000
	v_med3_f32 v98, v98, s29, v245
	v_mul_f32_e32 v98, 0x3fb8aa3b, v98
	v_lshlrev_b32_e32 v111, 16, v52
	v_exp_f32_e32 v110, v98
	v_max_f32_e64 v98, -v111, -v111
	v_med3_f32 v98, v98, s29, v245
	v_mul_f32_e32 v98, 0x3fb8aa3b, v98
	v_exp_f32_e32 v111, v98
	v_add_f32_e32 v98, 1.0, v110
	v_rcp_f32_e32 v131, v98
	s_mov_b32 s28, 0x800000
	v_add_f32_e32 v98, 1.0, v111
	v_rcp_f32_e32 v132, v98
	s_mov_b32 s30, 0x3f317217
	s_mov_b32 s31, 0x7f800000
	v_and_b32_e32 v107, 0xffff0000, v44
	v_and_b32_e32 v112, 0xffff0000, v52
	v_lshlrev_b32_e32 v108, 16, v45
	v_lshlrev_b32_e32 v109, 16, v53
	v_and_b32_e32 v105, 0xffff0000, v45
	v_and_b32_e32 v106, 0xffff0000, v53
	v_lshlrev_b32_e32 v103, 16, v46
	v_lshlrev_b32_e32 v104, 16, v54
	v_and_b32_e32 v101, 0xffff0000, v46
	v_and_b32_e32 v102, 0xffff0000, v54
	v_lshlrev_b32_e32 v99, 16, v47
	v_lshlrev_b32_e32 v100, 16, v55
	v_and_b32_e32 v96, 0xffff0000, v47
	v_and_b32_e32 v97, 0xffff0000, v55
	v_add_u32_e32 v149, s35, v144
	s_barrier
	v_sub_f32_e32 v172, 1.0, v84
	v_sub_f32_e32 v133, 1.0, v92
	v_fma_f32 v92, v131, v133, v92
	v_max_f32_e32 v92, 0xda24260, v92
	v_sub_f32_e32 v134, 1.0, v88
	v_fma_f32 v88, v132, v134, v88
	v_log_f32_e32 v92, v92
	v_max_f32_e32 v88, 0xda24260, v88
	v_sub_f32_e32 v154, 1.0, v93
	v_sub_f32_e32 v155, 1.0, v89
	v_mul_f32_e32 v98, 0x3f317217, v92
	v_fma_f32 v98, v92, s30, -v98
	v_fmac_f32_e32 v98, 0x3377d1cf, v92
	v_fmac_f32_e32 v98, 0x3f317217, v92
	v_cmp_lt_f32_e64 s[0:1], |v92|, s31
	v_sub_f32_e32 v160, 1.0, v94
	v_sub_f32_e32 v161, 1.0, v90
	v_cndmask_b32_e64 v92, v92, v98, s[0:1]
	v_sub_f32_e32 v166, 1.0, v95
	v_log_f32_e32 v88, v88
	v_sub_f32_e32 v167, 1.0, v91
	v_sub_f32_e32 v173, 1.0, v80
	v_sub_f32_e32 v178, 1.0, v85
	v_mul_f32_e32 v98, 0x3f317217, v88
	v_fma_f32 v98, v88, s30, -v98
	v_fmac_f32_e32 v98, 0x3377d1cf, v88
	v_fmac_f32_e32 v98, 0x3f317217, v88
	v_cmp_lt_f32_e64 s[0:1], |v88|, s31
	v_sub_f32_e32 v179, 1.0, v81
	v_sub_f32_e32 v184, 1.0, v86
	v_cndmask_b32_e64 v88, v88, v98, s[0:1]
	v_mov_b32_e32 v98, v88
	v_max_f32_e64 v88, -v107, -v107
	v_med3_f32 v88, v88, s29, v245
	v_mul_f32_e32 v88, 0x3fb8aa3b, v88
	v_exp_f32_e32 v135, v88
	v_max_f32_e64 v88, -v112, -v112
	v_med3_f32 v88, v88, s29, v245
	v_mul_f32_e32 v88, 0x3fb8aa3b, v88
	v_exp_f32_e32 v151, v88
	v_add_f32_e32 v88, 1.0, v135
	v_rcp_f32_e32 v152, v88
	v_sub_f32_e32 v185, 1.0, v82
	v_add_f32_e32 v88, 1.0, v151
	v_rcp_f32_e32 v153, v88
	v_fma_f32 v88, v152, v154, v93
	v_max_f32_e32 v88, 0xda24260, v88
	v_sub_f32_e32 v190, 1.0, v87
	v_sub_f32_e32 v191, 1.0, v83
	v_log_f32_e32 v88, v88
	s_nop 0
	v_mul_f32_e32 v93, 0x3f317217, v88
	v_fma_f32 v93, v88, s30, -v93
	v_fmac_f32_e32 v93, 0x3377d1cf, v88
	v_fmac_f32_e32 v93, 0x3f317217, v88
	v_cmp_lt_f32_e64 s[0:1], |v88|, s31
	s_nop 1
	v_cndmask_b32_e64 v88, v88, v93, s[0:1]
	v_mov_b32_e32 v93, v88
	v_fma_f32 v88, v153, v155, v89
	v_max_f32_e32 v88, 0xda24260, v88
	v_log_f32_e32 v88, v88
	s_nop 0
	v_mul_f32_e32 v89, 0x3f317217, v88
	v_fma_f32 v89, v88, s30, -v89
	v_fmac_f32_e32 v89, 0x3377d1cf, v88
	v_fmac_f32_e32 v89, 0x3f317217, v88
	v_cmp_lt_f32_e64 s[0:1], |v88|, s31
	s_nop 1
	v_cndmask_b32_e64 v88, v88, v89, s[0:1]
	v_mov_b32_e32 v107, v88
	v_max_f32_e64 v88, -v108, -v108
	v_med3_f32 v88, v88, s29, v245
	v_mul_f32_e32 v88, 0x3fb8aa3b, v88
	v_exp_f32_e32 v156, v88
	v_max_f32_e64 v88, -v109, -v109
	v_med3_f32 v88, v88, s29, v245
	v_mul_f32_e32 v88, 0x3fb8aa3b, v88
	v_exp_f32_e32 v157, v88
	v_add_f32_e32 v88, 1.0, v156
	v_rcp_f32_e32 v158, v88
	v_add_f32_e32 v88, 1.0, v157
	v_rcp_f32_e32 v159, v88
	v_fma_f32 v88, v158, v160, v94
	v_max_f32_e32 v88, 0xda24260, v88
	v_log_f32_e32 v88, v88
	s_nop 0
	v_mul_f32_e32 v89, 0x3f317217, v88
	v_fma_f32 v89, v88, s30, -v89
	v_fmac_f32_e32 v89, 0x3377d1cf, v88
	v_fmac_f32_e32 v89, 0x3f317217, v88
	v_cmp_lt_f32_e64 s[0:1], |v88|, s31
	s_nop 1
	v_cndmask_b32_e64 v88, v88, v89, s[0:1]
	v_fma_f32 v89, v159, v161, v90
	v_max_f32_e32 v89, 0xda24260, v89
	v_log_f32_e32 v89, v89
	s_nop 0
	v_mul_f32_e32 v90, 0x3f317217, v89
	v_fma_f32 v90, v89, s30, -v90
	v_fmac_f32_e32 v90, 0x3377d1cf, v89
	v_fmac_f32_e32 v90, 0x3f317217, v89
	v_cmp_lt_f32_e64 s[0:1], |v89|, s31
	s_nop 1
	v_cndmask_b32_e64 v89, v89, v90, s[0:1]
	v_mov_b32_e32 v90, v89
	v_max_f32_e64 v89, -v105, -v105
	v_med3_f32 v89, v89, s29, v245
	v_mul_f32_e32 v89, 0x3fb8aa3b, v89
	v_exp_f32_e32 v162, v89
	v_max_f32_e64 v89, -v106, -v106
	v_med3_f32 v89, v89, s29, v245
	v_mul_f32_e32 v89, 0x3fb8aa3b, v89
	v_exp_f32_e32 v163, v89
	v_add_f32_e32 v89, 1.0, v162
	v_rcp_f32_e32 v164, v89
	ds_bpermute_b32 v105, v138, v93
	v_add_f32_e32 v89, 1.0, v163
	v_rcp_f32_e32 v165, v89
	v_fmac_f32_e32 v95, v164, v166
	v_max_f32_e32 v89, 0xda24260, v95
	v_fmac_f32_e32 v91, v165, v167
	v_max_f32_e32 v91, 0xda24260, v91
	v_log_f32_e32 v89, v89
	ds_bpermute_b32 v95, v139, v98
	v_mul_f32_e32 v94, 0x3f317217, v89
	v_fma_f32 v94, v89, s30, -v94
	v_fmac_f32_e32 v94, 0x3377d1cf, v89
	v_fmac_f32_e32 v94, 0x3f317217, v89
	v_cmp_lt_f32_e64 s[0:1], |v89|, s31
	s_waitcnt lgkmcnt(0)
; DI float frcp(float x) { return __builtin_amdgcn_rcpf(x); }
; DI void phase_prep(int l, int wv, bool last, bool dry = false) {
;     ...
;             for (int i = 0; i < 8; ++i) { const float lbf = i < 4 ? lfa[i & 3] : lfc[i & 3], lbb = i < 4 ? lba[i & 3] : lbc[i & 3];
;                 const float ef = __expf(fminf(fmaxf(-zf[i], -80.f), 80.f)), eb = __expf(fminf(fmaxf(-zb[i], -80.f), 80.f)), sf = frcp(1.0f + ef), sb = frcp(1.0f + eb);
;                 lff[i] = __logf(fmaxf(lbf + (1.0f - lbf) * sf, F_MIN)); kf[i] = (1.0f - lbf) * (ef * sf);
;                 lfb[i] = __logf(fmaxf(lbb + (1.0f - lbb) * sb, F_MIN)); kb[i] = (1.0f - lbb) * (eb * sb);
;                 qs[i] = q[i] * frcp(1.0f + __expf(-q[i])) * QSCALE; }
;         }
; #pragma unroll
;         for (int d = 1; d < 8; d <<= 1) {
; #pragma unroll
;             for (int i = 0; i < 8; ++i) { const float o = __shfl_up(lff[i], 8 * d); if (pl >= d) lff[i] += o; const float o2 = __shfl_down(lfb[i], 8 * d); if (pl + d < 8) lfb[i] += o2; } }
	v_cndmask_b32_e64 v95, v247, v95, s[40:41]
	v_add_f32_e32 v95, v95, v98
	v_cndmask_b32_e64 v89, v89, v94, s[0:1]
	ds_bpermute_b32 v108, v138, v89
	v_log_f32_e32 v91, v91
	s_nop 0
	v_mul_f32_e32 v94, 0x3f317217, v91
	v_fma_f32 v94, v91, s30, -v94
	v_fmac_f32_e32 v94, 0x3377d1cf, v91
	v_fmac_f32_e32 v94, 0x3f317217, v91
	v_cmp_lt_f32_e64 s[0:1], |v91|, s31
	s_nop 1
	v_cndmask_b32_e64 v91, v91, v94, s[0:1]
	v_max_f32_e64 v94, -v103, -v103
	v_med3_f32 v94, v94, s29, v245
	v_mul_f32_e32 v94, 0x3fb8aa3b, v94
	v_exp_f32_e32 v168, v94
	v_max_f32_e64 v94, -v104, -v104
	v_med3_f32 v94, v94, s29, v245
	v_mul_f32_e32 v94, 0x3fb8aa3b, v94
	v_exp_f32_e32 v169, v94
	v_add_f32_e32 v94, 1.0, v168
	v_rcp_f32_e32 v170, v94
	v_add_f32_e32 v94, 1.0, v169
	v_rcp_f32_e32 v171, v94
	v_fma_f32 v84, v170, v172, v84
	v_max_f32_e32 v84, 0xda24260, v84
	v_fma_f32 v80, v171, v173, v80
	v_max_f32_e32 v80, 0xda24260, v80
	v_log_f32_e32 v84, v84
	s_nop 0
	v_mul_f32_e32 v94, 0x3f317217, v84
	v_fma_f32 v94, v84, s30, -v94
	v_fmac_f32_e32 v94, 0x3377d1cf, v84
	v_fmac_f32_e32 v94, 0x3f317217, v84
	v_cmp_lt_f32_e64 s[0:1], |v84|, s31
	s_nop 1
	v_cndmask_b32_e64 v84, v84, v94, s[0:1]
	ds_bpermute_b32 v109, v138, v84
	v_log_f32_e32 v80, v80
	s_nop 0
	v_mul_f32_e32 v94, 0x3f317217, v80
	v_fma_f32 v94, v80, s30, -v94
	v_fmac_f32_e32 v94, 0x3377d1cf, v80
	v_fmac_f32_e32 v94, 0x3f317217, v80
	v_cmp_lt_f32_e64 s[0:1], |v80|, s31
	s_nop 1
	v_cndmask_b32_e64 v80, v80, v94, s[0:1]
	v_max_f32_e64 v94, -v101, -v101
	v_med3_f32 v94, v94, s29, v245
	v_mul_f32_e32 v94, 0x3fb8aa3b, v94
	v_exp_f32_e32 v174, v94
	v_max_f32_e64 v94, -v102, -v102
	v_med3_f32 v94, v94, s29, v245
	v_mul_f32_e32 v94, 0x3fb8aa3b, v94
	v_exp_f32_e32 v175, v94
	v_add_f32_e32 v94, 1.0, v174
	v_rcp_f32_e32 v176, v94
	v_add_f32_e32 v94, 1.0, v175
	v_rcp_f32_e32 v177, v94
	v_fma_f32 v85, v176, v178, v85
	v_max_f32_e32 v85, 0xda24260, v85
	v_fma_f32 v81, v177, v179, v81
	v_max_f32_e32 v81, 0xda24260, v81
	v_log_f32_e32 v85, v85
	s_nop 0
	v_mul_f32_e32 v94, 0x3f317217, v85
	v_fma_f32 v94, v85, s30, -v94
	v_fmac_f32_e32 v94, 0x3377d1cf, v85
	v_fmac_f32_e32 v94, 0x3f317217, v85
	v_cmp_lt_f32_e64 s[0:1], |v85|, s31
	s_nop 1
	v_cndmask_b32_e64 v85, v85, v94, s[0:1]
	ds_bpermute_b32 v112, v138, v85
	v_log_f32_e32 v81, v81
	s_nop 0
	v_mul_f32_e32 v94, 0x3f317217, v81
	v_fma_f32 v94, v81, s30, -v94
	v_fmac_f32_e32 v94, 0x3377d1cf, v81
	v_fmac_f32_e32 v94, 0x3f317217, v81
	v_cmp_lt_f32_e64 s[0:1], |v81|, s31
	s_nop 1
	v_cndmask_b32_e64 v81, v81, v94, s[0:1]
	v_max_f32_e64 v94, -v99, -v99
	v_med3_f32 v94, v94, s29, v245
	v_mul_f32_e32 v94, 0x3fb8aa3b, v94
	v_exp_f32_e32 v180, v94
	v_max_f32_e64 v94, -v100, -v100
	v_med3_f32 v94, v94, s29, v245
	v_mul_f32_e32 v94, 0x3fb8aa3b, v94
	v_exp_f32_e32 v181, v94
	v_add_f32_e32 v94, 1.0, v180
	v_rcp_f32_e32 v182, v94
	v_add_f32_e32 v94, 1.0, v181
	v_rcp_f32_e32 v183, v94
	v_fma_f32 v86, v182, v184, v86
	v_max_f32_e32 v86, 0xda24260, v86
	v_fma_f32 v82, v183, v185, v82
	v_max_f32_e32 v82, 0xda24260, v82
	v_log_f32_e32 v86, v86
	s_nop 0
	v_mul_f32_e32 v94, 0x3f317217, v86
	v_fma_f32 v94, v86, s30, -v94
	v_fmac_f32_e32 v94, 0x3377d1cf, v86
	v_fmac_f32_e32 v94, 0x3f317217, v86
	v_cmp_lt_f32_e64 s[0:1], |v86|, s31
	s_nop 1
	v_cndmask_b32_e64 v86, v86, v94, s[0:1]
	ds_bpermute_b32 v114, v138, v86
	v_log_f32_e32 v82, v82
	s_nop 0
	v_mul_f32_e32 v94, 0x3f317217, v82
	v_fma_f32 v94, v82, s30, -v94
	v_fmac_f32_e32 v94, 0x3377d1cf, v82
	v_fmac_f32_e32 v94, 0x3f317217, v82
	v_cmp_lt_f32_e64 s[0:1], |v82|, s31
	s_nop 1
	v_cndmask_b32_e64 v82, v82, v94, s[0:1]
	v_max_f32_e64 v94, -v96, -v96
	v_med3_f32 v94, v94, s29, v245
	v_mul_f32_e32 v94, 0x3fb8aa3b, v94
	ds_bpermute_b32 v96, v139, v107
	v_exp_f32_e32 v186, v94
	v_max_f32_e64 v94, -v97, -v97
	v_med3_f32 v94, v94, s29, v245
	v_mul_f32_e32 v94, 0x3fb8aa3b, v94
	v_exp_f32_e32 v187, v94
	v_add_f32_e32 v94, 1.0, v186
	s_waitcnt lgkmcnt(0)
	v_cndmask_b32_e64 v96, v247, v96, s[40:41]
	v_rcp_f32_e32 v188, v94
	v_add_f32_e32 v97, v107, v96
	ds_bpermute_b32 v96, v139, v90
	v_add_f32_e32 v94, 1.0, v187
	v_fmac_f32_e32 v87, v188, v190
	v_max_f32_e32 v87, 0xda24260, v87
	s_waitcnt lgkmcnt(0)
	v_cndmask_b32_e64 v96, v247, v96, s[40:41]
	v_add_f32_e32 v90, v90, v96
	ds_bpermute_b32 v96, v139, v91
	v_rcp_f32_e32 v189, v94
	v_log_f32_e32 v87, v87
	s_waitcnt lgkmcnt(0)
; #define LAS __attribute__((address_space(3)))
; DI float frcp(float x) { return __builtin_amdgcn_rcpf(x); }
; DI void phase_prep(int l, int wv, bool last, bool dry = false) {
;     ...
;                 lff[i] = __logf(fmaxf(lbf + (1.0f - lbf) * sf, F_MIN)); kf[i] = (1.0f - lbf) * (ef * sf);
;                 lfb[i] = __logf(fmaxf(lbb + (1.0f - lbb) * sb, F_MIN)); kb[i] = (1.0f - lbb) * (eb * sb);
;                 qs[i] = q[i] * frcp(1.0f + __expf(-q[i])) * QSCALE; }
;         }
; #pragma unroll
;         for (int d = 1; d < 8; d <<= 1) {
; #pragma unroll
;             for (int i = 0; i < 8; ++i) { const float o = __shfl_up(lff[i], 8 * d); if (pl >= d) lff[i] += o; const float o2 = __shfl_down(lfb[i], 8 * d); if (pl + d < 8) lfb[i] += o2; } }
;         __syncthreads();
;         if (pl == 7) { *(LAS f32x4*)(L + O_TOTF + (w * 64 + cg * 8) * 4) = (f32x4){lff[0], lff[1], lff[2], lff[3]}; *(LAS f32x4*)(L + O_TOTF + (w * 64 + cg * 8 + 4) * 4) = (f32x4){lff[4], lff[5], lff[6], lff[7]}; }
	v_cndmask_b32_e64 v96, v247, v96, s[40:41]
	v_add_f32_e32 v91, v91, v96
	ds_bpermute_b32 v96, v139, v80
	v_mul_f32_e32 v94, 0x3f317217, v87
	v_fma_f32 v94, v87, s30, -v94
	v_fmac_f32_e32 v94, 0x3377d1cf, v87
	v_fmac_f32_e32 v83, v189, v191
	v_fmac_f32_e32 v94, 0x3f317217, v87
	v_cmp_lt_f32_e64 s[0:1], |v87|, s31
	v_max_f32_e32 v83, 0xda24260, v83
	s_waitcnt lgkmcnt(0)
	v_cndmask_b32_e64 v96, v247, v96, s[40:41]
	v_cndmask_b32_e64 v87, v87, v94, s[0:1]
	v_add_f32_e32 v80, v80, v96
	ds_bpermute_b32 v96, v139, v81
	v_log_f32_e32 v83, v83
	ds_bpermute_b32 v107, v138, v88
	ds_bpermute_b32 v115, v138, v87
	s_waitcnt lgkmcnt(2)
	v_cndmask_b32_e64 v96, v247, v96, s[40:41]
	v_mul_f32_e32 v94, 0x3f317217, v83
	v_add_f32_e32 v81, v81, v96
	ds_bpermute_b32 v96, v139, v82
	v_fma_f32 v94, v83, s30, -v94
	v_fmac_f32_e32 v94, 0x3377d1cf, v83
	v_fmac_f32_e32 v94, 0x3f317217, v83
	v_cmp_lt_f32_e64 s[0:1], |v83|, s31
	s_waitcnt lgkmcnt(0)
	v_cndmask_b32_e64 v96, v247, v96, s[40:41]
	v_add_f32_e32 v82, v82, v96
	v_cndmask_b32_e64 v83, v83, v94, s[0:1]
	ds_bpermute_b32 v96, v139, v83
	ds_bpermute_b32 v94, v138, v92
	s_waitcnt lgkmcnt(1)
	v_cndmask_b32_e64 v96, v247, v96, s[40:41]
	v_add_f32_e32 v83, v83, v96
	ds_bpermute_b32 v96, v141, v95
	s_waitcnt lgkmcnt(0)
	v_add_f32_e32 v96, v95, v96
	v_cndmask_b32_e64 v96, v95, v96, s[44:45]
	ds_bpermute_b32 v95, v141, v97
	ds_bpermute_b32 v104, v143, v96
	s_waitcnt lgkmcnt(1)
	v_add_f32_e32 v95, v97, v95
	v_cndmask_b32_e64 v97, v97, v95, s[44:45]
	ds_bpermute_b32 v95, v141, v90
	ds_bpermute_b32 v106, v143, v97
	s_waitcnt lgkmcnt(1)
	v_add_f32_e32 v95, v90, v95
	v_cndmask_b32_e64 v98, v90, v95, s[44:45]
	ds_bpermute_b32 v90, v141, v91
	v_cndmask_b32_e64 v95, v115, v247, s[38:39]
	s_waitcnt lgkmcnt(0)
	v_add_f32_e32 v90, v91, v90
	v_cndmask_b32_e64 v99, v91, v90, s[44:45]
	ds_bpermute_b32 v90, v141, v80
	s_waitcnt lgkmcnt(0)
	v_add_f32_e32 v90, v80, v90
	v_cndmask_b32_e64 v100, v80, v90, s[44:45]
	ds_bpermute_b32 v80, v141, v81
	s_waitcnt lgkmcnt(0)
	v_add_f32_e32 v80, v81, v80
	v_cndmask_b32_e64 v101, v81, v80, s[44:45]
	ds_bpermute_b32 v80, v141, v82
	v_cndmask_b32_e64 v81, v105, v247, s[38:39]
	ds_bpermute_b32 v105, v143, v98
	ds_bpermute_b32 v113, v143, v101
	s_waitcnt lgkmcnt(2)
	v_add_f32_e32 v80, v82, v80
	v_cndmask_b32_e64 v102, v82, v80, s[44:45]
	ds_bpermute_b32 v80, v141, v83
	s_waitcnt lgkmcnt(0)
	v_add_f32_e32 v80, v83, v80
	v_cndmask_b32_e64 v103, v83, v80, s[44:45]
	v_cndmask_b32_e64 v80, v94, v247, s[38:39]
	v_pk_add_f32 v[80:81], v[92:93], v[80:81]
	ds_bpermute_b32 v82, v140, v80
	ds_bpermute_b32 v83, v140, v81
	v_cndmask_b32_e64 v93, v112, v247, s[38:39]
	v_cndmask_b32_e64 v92, v109, v247, s[38:39]
	v_cndmask_b32_e64 v94, v114, v247, s[38:39]
	v_pk_add_f32 v[84:85], v[84:85], v[92:93]
	s_waitcnt lgkmcnt(0)
	v_pk_add_f32 v[82:83], v[80:81], v[82:83]
	v_pk_add_f32 v[86:87], v[86:87], v[94:95]
	v_cndmask_b32_e64 v91, v83, v81, s[42:43]
	v_cndmask_b32_e64 v90, v82, v80, s[42:43]
	v_cndmask_b32_e64 v83, v108, v247, s[38:39]
	v_cndmask_b32_e64 v82, v107, v247, s[38:39]
	v_pk_add_f32 v[82:83], v[88:89], v[82:83]
	ds_bpermute_b32 v88, v140, v82
	ds_bpermute_b32 v89, v140, v83
	ds_bpermute_b32 v92, v140, v84
	ds_bpermute_b32 v93, v140, v85
	ds_bpermute_b32 v94, v140, v86
	ds_bpermute_b32 v95, v140, v87
	s_waitcnt lgkmcnt(4)
	v_pk_add_f32 v[88:89], v[82:83], v[88:89]
	ds_bpermute_b32 v80, v142, v90
	s_waitcnt lgkmcnt(3)
	v_pk_add_f32 v[92:93], v[84:85], v[92:93]
	v_cndmask_b32_e64 v89, v89, v83, s[42:43]
	s_waitcnt lgkmcnt(1)
	v_pk_add_f32 v[94:95], v[86:87], v[94:95]
	v_cndmask_b32_e64 v88, v88, v82, s[42:43]
	v_cndmask_b32_e64 v93, v93, v85, s[42:43]
	v_cndmask_b32_e64 v92, v92, v84, s[42:43]
	v_cndmask_b32_e64 v95, v95, v87, s[42:43]
	v_cndmask_b32_e64 v94, v94, v86, s[42:43]
	ds_bpermute_b32 v81, v142, v91
	ds_bpermute_b32 v82, v142, v88
	ds_bpermute_b32 v83, v142, v89
	ds_bpermute_b32 v84, v142, v92
	ds_bpermute_b32 v85, v142, v93
	ds_bpermute_b32 v86, v142, v94
	ds_bpermute_b32 v87, v142, v95
	ds_bpermute_b32 v108, v143, v99
	ds_bpermute_b32 v107, v143, v100
	ds_bpermute_b32 v109, v143, v102
	ds_bpermute_b32 v115, v143, v103
	s_waitcnt lgkmcnt(10)
	v_pk_add_f32 v[80:81], v[90:91], v[80:81]
	s_waitcnt lgkmcnt(8)
	v_pk_add_f32 v[82:83], v[88:89], v[82:83]
	s_waitcnt lgkmcnt(6)
	v_pk_add_f32 v[84:85], v[92:93], v[84:85]
	s_waitcnt lgkmcnt(4)
	v_pk_add_f32 v[86:87], v[94:95], v[86:87]
	s_and_saveexec_b64 s[0:1], s[2:3]
	s_cbranch_execz .LBB0_375
	ds_write_b128 v149, v[80:83]
	ds_write_b128 v149, v[84:87] offset:16

; DI void unpack8(const u32x4 w, float (&f)[8]) { f[0] = bf_lo(w.x); f[1] = bf_hi(w.x); f[2] = bf_lo(w.y); f[3] = bf_hi(w.y); f[4] = bf_lo(w.z); f[5] = bf_hi(w.z); f[6] = bf_lo(w.w); f[7] = bf_hi(w.w); }
; DI float frcp(float x) { return __builtin_amdgcn_rcpf(x); }
; DI void phase_prep(int l, int wv, bool last, bool dry = false) {
;     ...
;     auto item_load = [&](int item, PrepIn& P) {
;         const int chunk = item >> 4, h = (item >> 1) & 7, hc = (item & 1) * 64 + cg * 8, row = chunk * 64 + pp, c0 = h * DK + hc;
;         const bf16* prow = F.PROJ + (size_t)row * INW;
;         bool hasp, hasn;
;         if (row < NLAT) { hasp = pp != 0; hasn = pp != 63; } else { const int t = (row - NLAT) & (CTXL - 1); hasp = t != 0; hasn = t != CTXL - 1; }
;         const bf16* pprev = hasp ? prow - INW : prow; const bf16* pnext = hasn ? prow + INW : prow;
;         if (!(last && row >= NLAT)) {
;     ...
;         P.ccp = *(const u32x4*)(pprev + C_CC + c0); P.cvp = *(const u32x4*)(pprev + C_CV + c0); P.ccn = *(const u32x4*)(pnext + C_CC + c0); P.cvn = *(const u32x4*)(pnext + C_CV + c0);
;         P.q = *(const u32x4*)(prow + C_Q + c0); }
;         P.zf = *(const u32x4*)(prow + C_ZF + c0); P.zb = *(const u32x4*)(prow + C_ZB + c0); };
;     ...
;         {   float zf[8], zb[8], q[8];
;             unpack8(P.zf, zf); unpack8(P.zb, zb);
;             if (full) unpack8(P.q, q); else {
; #pragma unroll
;                 for (int i = 0; i < 8; ++i) q[i] = 0.f; }
;             const f32x4 lfa = *(const f32x4*)(lbt + c0), lfc = *(const f32x4*)(lbt + c0 + 4), lba = *(const f32x4*)(lbt + DC + c0), lbc = *(const f32x4*)(lbt + DC + c0 + 4);
; #pragma unroll
;             for (int i = 0; i < 8; ++i) { const float lbf = i < 4 ? lfa[i & 3] : lfc[i & 3], lbb = i < 4 ? lba[i & 3] : lbc[i & 3];
;                 const float ef = __expf(fminf(fmaxf(-zf[i], -80.f), 80.f)), eb = __expf(fminf(fmaxf(-zb[i], -80.f), 80.f)), sf = frcp(1.0f + ef), sb = frcp(1.0f + eb);
;                 lff[i] = __logf(fmaxf(lbf + (1.0f - lbf) * sf, F_MIN)); kf[i] = (1.0f - lbf) * (ef * sf);
.LBB0_398:
	s_or_b64 exec, exec, s[26:27]
	v_mov_b32_e32 v121, 0
	v_mov_b32_e32 v122, 0
	v_mov_b32_e32 v123, 0
	v_mov_b32_e32 v124, 0
	v_mov_b32_e32 v125, 0
	v_mov_b32_e32 v126, 0
	v_mov_b32_e32 v127, 0
	v_mov_b32_e32 v130, 0
	s_and_saveexec_b64 s[0:1], s[24:25]
	v_lshlrev_b32_e32 v121, 16, v68
	v_and_b32_e32 v122, 0xffff0000, v68
	v_lshlrev_b32_e32 v123, 16, v69
	v_and_b32_e32 v124, 0xffff0000, v69
	v_lshlrev_b32_e32 v125, 16, v70
	v_and_b32_e32 v126, 0xffff0000, v70
	v_lshlrev_b32_e32 v127, 16, v71
	v_and_b32_e32 v130, 0xffff0000, v71
	s_or_b64 exec, exec, s[0:1]
	v_lshlrev_b32_e32 v88, 2, v128
	global_load_dwordx4 v[84:87], v88, s[12:13] offset:16
	global_load_dwordx4 v[92:95], v88, s[12:13]
	s_waitcnt lgkmcnt(0)
	global_load_dwordx4 v[80:83], v88, s[22:23] offset:16
	s_nop 0
	global_load_dwordx4 v[88:91], v88, s[22:23]
	v_lshlrev_b32_e32 v98, 16, v72
	v_max_f32_e64 v98, -v98, -v98
	s_mov_b32 s27, 0xc2a00000
	v_med3_f32 v98, v98, s27, v245
	v_mul_f32_e32 v98, 0x3fb8aa3b, v98
	v_lshlrev_b32_e32 v111, 16, v76
	v_exp_f32_e32 v110, v98
	v_max_f32_e64 v98, -v111, -v111
	v_med3_f32 v98, v98, s27, v245
	v_mul_f32_e32 v98, 0x3fb8aa3b, v98
	v_exp_f32_e32 v111, v98
	v_add_f32_e32 v98, 1.0, v110
	v_rcp_f32_e32 v131, v98
	s_mov_b32 s26, 0x800000
	v_add_f32_e32 v98, 1.0, v111
	v_rcp_f32_e32 v132, v98
	s_mov_b32 s28, 0x3f317217
	s_mov_b32 s29, 0x7f800000
	v_and_b32_e32 v107, 0xffff0000, v72
	v_and_b32_e32 v112, 0xffff0000, v76
	v_lshlrev_b32_e32 v108, 16, v73
	v_lshlrev_b32_e32 v109, 16, v77
	v_and_b32_e32 v105, 0xffff0000, v73
	v_and_b32_e32 v106, 0xffff0000, v77
	v_lshlrev_b32_e32 v103, 16, v74
	v_lshlrev_b32_e32 v104, 16, v78
	v_and_b32_e32 v101, 0xffff0000, v74
	v_and_b32_e32 v102, 0xffff0000, v78
	v_lshlrev_b32_e32 v99, 16, v75
	v_lshlrev_b32_e32 v100, 16, v79
	v_and_b32_e32 v96, 0xffff0000, v75
	v_and_b32_e32 v97, 0xffff0000, v79
	s_barrier
	s_waitcnt vmcnt(3)
	v_sub_f32_e32 v172, 1.0, v84
	s_waitcnt vmcnt(2)
	v_sub_f32_e32 v133, 1.0, v92
	v_fma_f32 v92, v131, v133, v92
	v_max_f32_e32 v92, 0xda24260, v92
	s_waitcnt vmcnt(0)
	v_sub_f32_e32 v134, 1.0, v88
	v_fma_f32 v88, v132, v134, v88
	v_log_f32_e32 v92, v92
	v_max_f32_e32 v88, 0xda24260, v88
	v_sub_f32_e32 v154, 1.0, v93
	v_sub_f32_e32 v155, 1.0, v89
	v_mul_f32_e32 v98, 0x3f317217, v92
	v_fma_f32 v98, v92, s28, -v98
	v_fmac_f32_e32 v98, 0x3377d1cf, v92
	v_fmac_f32_e32 v98, 0x3f317217, v92
	v_cmp_lt_f32_e64 s[0:1], |v92|, s29
	v_sub_f32_e32 v160, 1.0, v94
	v_sub_f32_e32 v161, 1.0, v90
	v_cndmask_b32_e64 v92, v92, v98, s[0:1]
	s_add_i32 s96, s59, s68
	s_cmpk_gt_i32 s96, 0x11ff
	s_cbranch_scc1 .Lprep_pf_skip_B
	v_mov_b32_e32 v209, 0
	s_add_i32 s97, s60, s63
	s_add_i32 s96, s58, s64
	s_andn2_b32 s97, s97, 63
	v_add_u32_e32 v47, s97, v136
	s_and_b32 s96, s96, 0x3c0
	v_mov_b64_e32 v[44:45], s[8:9]
	v_or_b32_e32 v46, s96, v137
	v_mad_i64_i32 v[44:45], s[96:97], v47, s66, v[44:45]
	v_readlane_b32 s96, v254, 33
	v_cmp_gt_i32_e32 vcc, s89, v47
	v_readlane_b32 s97, v254, 34
	s_or_b64 s[96:97], s[96:97], vcc
	s_and_saveexec_b64 s[94:95], s[96:97]
	s_xor_b64 s[94:95], exec, s[94:95]
	s_cbranch_execz .LBB0_391
	v_and_b32_e32 v0, 0xff, v47
	s_movk_i32 s96, 0xff
	v_cmp_gt_i32_e32 vcc, s89, v47
	v_cmp_ne_u32_e64 s[96:97], s96, v0
	v_cndmask_b32_e64 v2, 0, 1, s[36:37]
	v_cndmask_b32_e32 v1, v0, v136, vcc
	v_cndmask_b32_e64 v0, 0, 1, s[96:97]
	v_cndmask_b32_e32 v0, v0, v2, vcc
	v_and_b32_e32 v0, 1, v0
	v_cmp_eq_u32_e32 vcc, 1, v0
	s_nop 1
	v_cndmask_b32_e32 v208, 0, v241, vcc
	v_lshl_add_u64 v[16:17], v[44:45], 0, v[208:209]
	v_cmp_eq_u32_e32 vcc, 0, v1
	v_lshlrev_b32_e32 v208, 1, v46
	v_lshl_add_u64 v[10:11], v[44:45], 0, v[208:209]
	v_cndmask_b32_e64 v1, -1, 0, vcc
	v_cndmask_b32_e64 v0, v251, 0, vcc
	v_lshl_add_u64 v[8:9], v[44:45], 0, v[0:1]
	v_add_co_u32_e32 v28, vcc, s67, v10
	v_lshl_add_u64 v[8:9], v[8:9], 0, v[208:209]
	s_nop 0
	v_addc_co_u32_e32 v29, vcc, 0, v11, vcc
	v_add_co_u32_e32 v12, vcc, 0x1000, v8
	v_lshl_add_u64 v[16:17], v[16:17], 0, v[208:209]
	s_nop 0
	v_addc_co_u32_e32 v13, vcc, 0, v9, vcc
	v_add_co_u32_e32 v20, vcc, 0x1000, v16
	global_load_dwordx4 v[0:3], v[10:11], off
	global_load_dwordx4 v[4:7], v[10:11], off offset:2048
	v_addc_co_u32_e32 v21, vcc, 0, v17, vcc
	global_load_dwordx4 v[8:11], v[8:9], off offset:2048
	s_nop 0
	global_load_dwordx4 v[12:15], v[12:13], off
	s_nop 0
	global_load_dwordx4 v[16:19], v[16:17], off offset:2048
	s_nop 0
	global_load_dwordx4 v[24:27], v[20:21], off
	s_nop 0
	global_load_dwordx4 v[20:23], v[28:29], off
	s_nop 0
	global_load_dwordx4 v[28:31], v[28:29], off offset:2048

; DI float frcp(float x) { return __builtin_amdgcn_rcpf(x); }
; DI void phase_prep(int l, int wv, bool last, bool dry = false) {
;     ...
;             for (int i = 0; i < 8; ++i) { const float lbf = i < 4 ? lfa[i & 3] : lfc[i & 3], lbb = i < 4 ? lba[i & 3] : lbc[i & 3];
;                 const float ef = __expf(fminf(fmaxf(-zf[i], -80.f), 80.f)), eb = __expf(fminf(fmaxf(-zb[i], -80.f), 80.f)), sf = frcp(1.0f + ef), sb = frcp(1.0f + eb);
;                 lff[i] = __logf(fmaxf(lbf + (1.0f - lbf) * sf, F_MIN)); kf[i] = (1.0f - lbf) * (ef * sf);
;                 lfb[i] = __logf(fmaxf(lbb + (1.0f - lbb) * sb, F_MIN)); kb[i] = (1.0f - lbb) * (eb * sb);
;                 qs[i] = q[i] * frcp(1.0f + __expf(-q[i])) * QSCALE; }
;         }
; #pragma unroll
;         for (int d = 1; d < 8; d <<= 1) {
; #pragma unroll
;             for (int i = 0; i < 8; ++i) { const float o = __shfl_up(lff[i], 8 * d); if (pl >= d) lff[i] += o; const float o2 = __shfl_down(lfb[i], 8 * d); if (pl + d < 8) lfb[i] += o2; } }
.Lprep_pf_skip_B:
	v_sub_f32_e32 v166, 1.0, v95
	v_log_f32_e32 v88, v88
	v_sub_f32_e32 v167, 1.0, v91
	v_sub_f32_e32 v173, 1.0, v80
	v_sub_f32_e32 v178, 1.0, v85
	v_mul_f32_e32 v98, 0x3f317217, v88
	v_fma_f32 v98, v88, s28, -v98
	v_fmac_f32_e32 v98, 0x3377d1cf, v88
	v_fmac_f32_e32 v98, 0x3f317217, v88
	v_cmp_lt_f32_e64 s[0:1], |v88|, s29
	v_sub_f32_e32 v179, 1.0, v81
	v_sub_f32_e32 v184, 1.0, v86
	v_cndmask_b32_e64 v88, v88, v98, s[0:1]
	v_mov_b32_e32 v98, v88
	v_max_f32_e64 v88, -v107, -v107
	v_med3_f32 v88, v88, s27, v245
	v_mul_f32_e32 v88, 0x3fb8aa3b, v88
	v_exp_f32_e32 v135, v88
	v_max_f32_e64 v88, -v112, -v112
	v_med3_f32 v88, v88, s27, v245
	v_mul_f32_e32 v88, 0x3fb8aa3b, v88
	v_exp_f32_e32 v151, v88
	v_add_f32_e32 v88, 1.0, v135
	v_rcp_f32_e32 v152, v88
	v_sub_f32_e32 v185, 1.0, v82
	v_add_f32_e32 v88, 1.0, v151
	v_rcp_f32_e32 v153, v88
	v_fma_f32 v88, v152, v154, v93
	v_max_f32_e32 v88, 0xda24260, v88
	v_sub_f32_e32 v190, 1.0, v87
	v_sub_f32_e32 v191, 1.0, v83
	v_log_f32_e32 v88, v88
	s_nop 0
	v_mul_f32_e32 v93, 0x3f317217, v88
	v_fma_f32 v93, v88, s28, -v93
	v_fmac_f32_e32 v93, 0x3377d1cf, v88
	v_fmac_f32_e32 v93, 0x3f317217, v88
	v_cmp_lt_f32_e64 s[0:1], |v88|, s29
	s_nop 1
	v_cndmask_b32_e64 v88, v88, v93, s[0:1]
	v_mov_b32_e32 v93, v88
	v_fma_f32 v88, v153, v155, v89
	v_max_f32_e32 v88, 0xda24260, v88
	v_log_f32_e32 v88, v88
	s_nop 0
	v_mul_f32_e32 v89, 0x3f317217, v88
	v_fma_f32 v89, v88, s28, -v89
	v_fmac_f32_e32 v89, 0x3377d1cf, v88
	v_fmac_f32_e32 v89, 0x3f317217, v88
	v_cmp_lt_f32_e64 s[0:1], |v88|, s29
	s_nop 1
	v_cndmask_b32_e64 v88, v88, v89, s[0:1]
	v_mov_b32_e32 v107, v88
	v_max_f32_e64 v88, -v108, -v108
	v_med3_f32 v88, v88, s27, v245
	v_mul_f32_e32 v88, 0x3fb8aa3b, v88
	v_exp_f32_e32 v156, v88
	v_max_f32_e64 v88, -v109, -v109
	v_med3_f32 v88, v88, s27, v245
	v_mul_f32_e32 v88, 0x3fb8aa3b, v88
	v_exp_f32_e32 v157, v88
	v_add_f32_e32 v88, 1.0, v156
	v_rcp_f32_e32 v158, v88
	v_add_f32_e32 v88, 1.0, v157
	v_rcp_f32_e32 v159, v88
	v_fma_f32 v88, v158, v160, v94
	v_max_f32_e32 v88, 0xda24260, v88
	v_log_f32_e32 v88, v88
	s_nop 0
	v_mul_f32_e32 v89, 0x3f317217, v88
	v_fma_f32 v89, v88, s28, -v89
	v_fmac_f32_e32 v89, 0x3377d1cf, v88
	v_fmac_f32_e32 v89, 0x3f317217, v88
	v_cmp_lt_f32_e64 s[0:1], |v88|, s29
	s_nop 1
	v_cndmask_b32_e64 v88, v88, v89, s[0:1]
	v_fma_f32 v89, v159, v161, v90
	v_max_f32_e32 v89, 0xda24260, v89
	v_log_f32_e32 v89, v89
	s_nop 0
	v_mul_f32_e32 v90, 0x3f317217, v89
	v_fma_f32 v90, v89, s28, -v90
	v_fmac_f32_e32 v90, 0x3377d1cf, v89
	v_fmac_f32_e32 v90, 0x3f317217, v89
	v_cmp_lt_f32_e64 s[0:1], |v89|, s29
	s_nop 1
	v_cndmask_b32_e64 v89, v89, v90, s[0:1]
	v_mov_b32_e32 v90, v89
	v_max_f32_e64 v89, -v105, -v105
	v_med3_f32 v89, v89, s27, v245
	v_mul_f32_e32 v89, 0x3fb8aa3b, v89
	v_exp_f32_e32 v162, v89
	v_max_f32_e64 v89, -v106, -v106
	v_med3_f32 v89, v89, s27, v245
	v_mul_f32_e32 v89, 0x3fb8aa3b, v89
	v_exp_f32_e32 v163, v89
	v_add_f32_e32 v89, 1.0, v162
	v_rcp_f32_e32 v164, v89
	ds_bpermute_b32 v105, v138, v93
	v_add_f32_e32 v89, 1.0, v163
	v_rcp_f32_e32 v165, v89
	v_fmac_f32_e32 v95, v164, v166
	v_max_f32_e32 v89, 0xda24260, v95
	v_fmac_f32_e32 v91, v165, v167
	v_max_f32_e32 v91, 0xda24260, v91
	v_log_f32_e32 v89, v89
	ds_bpermute_b32 v95, v139, v98
	v_mul_f32_e32 v94, 0x3f317217, v89
	v_fma_f32 v94, v89, s28, -v94
	v_fmac_f32_e32 v94, 0x3377d1cf, v89
	v_fmac_f32_e32 v94, 0x3f317217, v89
	v_cmp_lt_f32_e64 s[0:1], |v89|, s29
	s_waitcnt lgkmcnt(0)
	v_cndmask_b32_e64 v95, v247, v95, s[40:41]
	v_add_f32_e32 v95, v95, v98
	v_cndmask_b32_e64 v89, v89, v94, s[0:1]
	ds_bpermute_b32 v108, v138, v89
	v_log_f32_e32 v91, v91
	s_nop 0
	v_mul_f32_e32 v94, 0x3f317217, v91
	v_fma_f32 v94, v91, s28, -v94
	v_fmac_f32_e32 v94, 0x3377d1cf, v91
	v_fmac_f32_e32 v94, 0x3f317217, v91
	v_cmp_lt_f32_e64 s[0:1], |v91|, s29
	s_nop 1
	v_cndmask_b32_e64 v91, v91, v94, s[0:1]
	v_max_f32_e64 v94, -v103, -v103
	v_med3_f32 v94, v94, s27, v245
	v_mul_f32_e32 v94, 0x3fb8aa3b, v94
	v_exp_f32_e32 v168, v94
	v_max_f32_e64 v94, -v104, -v104
	v_med3_f32 v94, v94, s27, v245
	v_mul_f32_e32 v94, 0x3fb8aa3b, v94
	v_exp_f32_e32 v169, v94
	v_add_f32_e32 v94, 1.0, v168
	v_rcp_f32_e32 v170, v94
	v_add_f32_e32 v94, 1.0, v169
	v_rcp_f32_e32 v171, v94
	v_fma_f32 v84, v170, v172, v84
	v_max_f32_e32 v84, 0xda24260, v84
	v_fma_f32 v80, v171, v173, v80
	v_max_f32_e32 v80, 0xda24260, v80
	v_log_f32_e32 v84, v84
	s_nop 0
	v_mul_f32_e32 v94, 0x3f317217, v84
	v_fma_f32 v94, v84, s28, -v94
	v_fmac_f32_e32 v94, 0x3377d1cf, v84
	v_fmac_f32_e32 v94, 0x3f317217, v84
	v_cmp_lt_f32_e64 s[0:1], |v84|, s29
	s_nop 1
	v_cndmask_b32_e64 v84, v84, v94, s[0:1]
	ds_bpermute_b32 v109, v138, v84
	v_log_f32_e32 v80, v80
	s_nop 0
	v_mul_f32_e32 v94, 0x3f317217, v80
	v_fma_f32 v94, v80, s28, -v94
	v_fmac_f32_e32 v94, 0x3377d1cf, v80
	v_fmac_f32_e32 v94, 0x3f317217, v80
	v_cmp_lt_f32_e64 s[0:1], |v80|, s29
	s_nop 1
	v_cndmask_b32_e64 v80, v80, v94, s[0:1]
	v_max_f32_e64 v94, -v101, -v101
	v_med3_f32 v94, v94, s27, v245
	v_mul_f32_e32 v94, 0x3fb8aa3b, v94
	v_exp_f32_e32 v174, v94
	v_max_f32_e64 v94, -v102, -v102
	v_med3_f32 v94, v94, s27, v245
	v_mul_f32_e32 v94, 0x3fb8aa3b, v94
	v_exp_f32_e32 v175, v94
	v_add_f32_e32 v94, 1.0, v174
	v_rcp_f32_e32 v176, v94
	v_add_f32_e32 v94, 1.0, v175
	v_rcp_f32_e32 v177, v94
	v_fma_f32 v85, v176, v178, v85
	v_max_f32_e32 v85, 0xda24260, v85
	v_fma_f32 v81, v177, v179, v81
	v_max_f32_e32 v81, 0xda24260, v81
	v_log_f32_e32 v85, v85
	s_nop 0
	v_mul_f32_e32 v94, 0x3f317217, v85
	v_fma_f32 v94, v85, s28, -v94
	v_fmac_f32_e32 v94, 0x3377d1cf, v85
	v_fmac_f32_e32 v94, 0x3f317217, v85
	v_cmp_lt_f32_e64 s[0:1], |v85|, s29
	s_nop 1
; #define LAS __attribute__((address_space(3)))
; DI float frcp(float x) { return __builtin_amdgcn_rcpf(x); }
; DI void phase_prep(int l, int wv, bool last, bool dry = false) {
;     ...
;                 lff[i] = __logf(fmaxf(lbf + (1.0f - lbf) * sf, F_MIN)); kf[i] = (1.0f - lbf) * (ef * sf);
;                 lfb[i] = __logf(fmaxf(lbb + (1.0f - lbb) * sb, F_MIN)); kb[i] = (1.0f - lbb) * (eb * sb);
;                 qs[i] = q[i] * frcp(1.0f + __expf(-q[i])) * QSCALE; }
;         }
; #pragma unroll
;         for (int d = 1; d < 8; d <<= 1) {
; #pragma unroll
;             for (int i = 0; i < 8; ++i) { const float o = __shfl_up(lff[i], 8 * d); if (pl >= d) lff[i] += o; const float o2 = __shfl_down(lfb[i], 8 * d); if (pl + d < 8) lfb[i] += o2; } }
;         __syncthreads();
;         if (pl == 7) { *(LAS f32x4*)(L + O_TOTF + (w * 64 + cg * 8) * 4) = (f32x4){lff[0], lff[1], lff[2], lff[3]}; *(LAS f32x4*)(L + O_TOTF + (w * 64 + cg * 8 + 4) * 4) = (f32x4){lff[4], lff[5], lff[6], lff[7]}; }
	v_cndmask_b32_e64 v85, v85, v94, s[0:1]
	ds_bpermute_b32 v112, v138, v85
	v_log_f32_e32 v81, v81
	s_nop 0
	v_mul_f32_e32 v94, 0x3f317217, v81
	v_fma_f32 v94, v81, s28, -v94
	v_fmac_f32_e32 v94, 0x3377d1cf, v81
	v_fmac_f32_e32 v94, 0x3f317217, v81
	v_cmp_lt_f32_e64 s[0:1], |v81|, s29
	s_nop 1
	v_cndmask_b32_e64 v81, v81, v94, s[0:1]
	v_max_f32_e64 v94, -v99, -v99
	v_med3_f32 v94, v94, s27, v245
	v_mul_f32_e32 v94, 0x3fb8aa3b, v94
	v_exp_f32_e32 v180, v94
	v_max_f32_e64 v94, -v100, -v100
	v_med3_f32 v94, v94, s27, v245
	v_mul_f32_e32 v94, 0x3fb8aa3b, v94
	v_exp_f32_e32 v181, v94
	v_add_f32_e32 v94, 1.0, v180
	v_rcp_f32_e32 v182, v94
	v_add_f32_e32 v94, 1.0, v181
	v_rcp_f32_e32 v183, v94
	v_fma_f32 v86, v182, v184, v86
	v_max_f32_e32 v86, 0xda24260, v86
	v_fma_f32 v82, v183, v185, v82
	v_max_f32_e32 v82, 0xda24260, v82
	v_log_f32_e32 v86, v86
	s_nop 0
	v_mul_f32_e32 v94, 0x3f317217, v86
	v_fma_f32 v94, v86, s28, -v94
	v_fmac_f32_e32 v94, 0x3377d1cf, v86
	v_fmac_f32_e32 v94, 0x3f317217, v86
	v_cmp_lt_f32_e64 s[0:1], |v86|, s29
	s_nop 1
	v_cndmask_b32_e64 v86, v86, v94, s[0:1]
	ds_bpermute_b32 v114, v138, v86
	v_log_f32_e32 v82, v82
	s_nop 0
	v_mul_f32_e32 v94, 0x3f317217, v82
	v_fma_f32 v94, v82, s28, -v94
	v_fmac_f32_e32 v94, 0x3377d1cf, v82
	v_fmac_f32_e32 v94, 0x3f317217, v82
	v_cmp_lt_f32_e64 s[0:1], |v82|, s29
	s_nop 1
	v_cndmask_b32_e64 v82, v82, v94, s[0:1]
	v_max_f32_e64 v94, -v96, -v96
	v_med3_f32 v94, v94, s27, v245
	v_mul_f32_e32 v94, 0x3fb8aa3b, v94
	ds_bpermute_b32 v96, v139, v107
	v_exp_f32_e32 v186, v94
	v_max_f32_e64 v94, -v97, -v97
	v_med3_f32 v94, v94, s27, v245
	v_mul_f32_e32 v94, 0x3fb8aa3b, v94
	v_exp_f32_e32 v187, v94
	v_add_f32_e32 v94, 1.0, v186
	s_waitcnt lgkmcnt(0)
	v_cndmask_b32_e64 v96, v247, v96, s[40:41]
	v_rcp_f32_e32 v188, v94
	v_add_f32_e32 v97, v107, v96
	ds_bpermute_b32 v96, v139, v90
	v_add_f32_e32 v94, 1.0, v187
	v_fmac_f32_e32 v87, v188, v190
	v_max_f32_e32 v87, 0xda24260, v87
	s_waitcnt lgkmcnt(0)
	v_cndmask_b32_e64 v96, v247, v96, s[40:41]
	v_add_f32_e32 v90, v90, v96
	ds_bpermute_b32 v96, v139, v91
	v_rcp_f32_e32 v189, v94
	v_log_f32_e32 v87, v87
	s_waitcnt lgkmcnt(0)
	v_cndmask_b32_e64 v96, v247, v96, s[40:41]
	v_add_f32_e32 v91, v91, v96
	ds_bpermute_b32 v96, v139, v80
	v_mul_f32_e32 v94, 0x3f317217, v87
	v_fma_f32 v94, v87, s28, -v94
	v_fmac_f32_e32 v94, 0x3377d1cf, v87
	v_fmac_f32_e32 v83, v189, v191
	v_fmac_f32_e32 v94, 0x3f317217, v87
	v_cmp_lt_f32_e64 s[0:1], |v87|, s29
	v_max_f32_e32 v83, 0xda24260, v83
	s_waitcnt lgkmcnt(0)
	v_cndmask_b32_e64 v96, v247, v96, s[40:41]
	v_cndmask_b32_e64 v87, v87, v94, s[0:1]
	v_add_f32_e32 v80, v80, v96
	ds_bpermute_b32 v96, v139, v81
	v_log_f32_e32 v83, v83
	ds_bpermute_b32 v107, v138, v88
	ds_bpermute_b32 v115, v138, v87
	s_waitcnt lgkmcnt(2)
	v_cndmask_b32_e64 v96, v247, v96, s[40:41]
	v_mul_f32_e32 v94, 0x3f317217, v83
	v_add_f32_e32 v81, v81, v96
	ds_bpermute_b32 v96, v139, v82
	v_fma_f32 v94, v83, s28, -v94
	v_fmac_f32_e32 v94, 0x3377d1cf, v83
	v_fmac_f32_e32 v94, 0x3f317217, v83
	v_cmp_lt_f32_e64 s[0:1], |v83|, s29
	s_waitcnt lgkmcnt(0)
	v_cndmask_b32_e64 v96, v247, v96, s[40:41]
	v_add_f32_e32 v82, v82, v96
	v_cndmask_b32_e64 v83, v83, v94, s[0:1]
	ds_bpermute_b32 v96, v139, v83
	ds_bpermute_b32 v94, v138, v92
	s_waitcnt lgkmcnt(1)
	v_cndmask_b32_e64 v96, v247, v96, s[40:41]
	v_add_f32_e32 v83, v83, v96
	ds_bpermute_b32 v96, v141, v95
	s_waitcnt lgkmcnt(0)
	v_add_f32_e32 v96, v95, v96
	v_cndmask_b32_e64 v96, v95, v96, s[44:45]
	ds_bpermute_b32 v95, v141, v97
	ds_bpermute_b32 v104, v143, v96
	s_waitcnt lgkmcnt(1)
	v_add_f32_e32 v95, v97, v95
	v_cndmask_b32_e64 v97, v97, v95, s[44:45]
	ds_bpermute_b32 v95, v141, v90
	ds_bpermute_b32 v106, v143, v97
	s_waitcnt lgkmcnt(1)
	v_add_f32_e32 v95, v90, v95
	v_cndmask_b32_e64 v98, v90, v95, s[44:45]
	ds_bpermute_b32 v90, v141, v91
	v_cndmask_b32_e64 v95, v115, v247, s[38:39]
	s_waitcnt lgkmcnt(0)
	v_add_f32_e32 v90, v91, v90
	v_cndmask_b32_e64 v99, v91, v90, s[44:45]
	ds_bpermute_b32 v90, v141, v80
	s_waitcnt lgkmcnt(0)
	v_add_f32_e32 v90, v80, v90
	v_cndmask_b32_e64 v100, v80, v90, s[44:45]
	ds_bpermute_b32 v80, v141, v81
	s_waitcnt lgkmcnt(0)
	v_add_f32_e32 v80, v81, v80
	v_cndmask_b32_e64 v101, v81, v80, s[44:45]
	ds_bpermute_b32 v80, v141, v82
	v_cndmask_b32_e64 v81, v105, v247, s[38:39]
	ds_bpermute_b32 v105, v143, v98
	ds_bpermute_b32 v113, v143, v101
	s_waitcnt lgkmcnt(2)
	v_add_f32_e32 v80, v82, v80
	v_cndmask_b32_e64 v102, v82, v80, s[44:45]
	ds_bpermute_b32 v80, v141, v83
	s_waitcnt lgkmcnt(0)
	v_add_f32_e32 v80, v83, v80
	v_cndmask_b32_e64 v103, v83, v80, s[44:45]
	v_cndmask_b32_e64 v80, v94, v247, s[38:39]
	v_pk_add_f32 v[80:81], v[92:93], v[80:81]
	ds_bpermute_b32 v82, v140, v80
	ds_bpermute_b32 v83, v140, v81
	v_cndmask_b32_e64 v93, v112, v247, s[38:39]
	v_cndmask_b32_e64 v92, v109, v247, s[38:39]
	v_cndmask_b32_e64 v94, v114, v247, s[38:39]
	v_pk_add_f32 v[84:85], v[84:85], v[92:93]
	s_waitcnt lgkmcnt(0)
	v_pk_add_f32 v[82:83], v[80:81], v[82:83]
	v_pk_add_f32 v[86:87], v[86:87], v[94:95]
	v_cndmask_b32_e64 v91, v83, v81, s[42:43]
	v_cndmask_b32_e64 v90, v82, v80, s[42:43]
	v_cndmask_b32_e64 v83, v108, v247, s[38:39]
	v_cndmask_b32_e64 v82, v107, v247, s[38:39]
	v_pk_add_f32 v[82:83], v[88:89], v[82:83]
	ds_bpermute_b32 v88, v140, v82
	ds_bpermute_b32 v89, v140, v83
	ds_bpermute_b32 v92, v140, v84
	ds_bpermute_b32 v93, v140, v85
	ds_bpermute_b32 v94, v140, v86
	ds_bpermute_b32 v95, v140, v87
	s_waitcnt lgkmcnt(4)
	v_pk_add_f32 v[88:89], v[82:83], v[88:89]
	ds_bpermute_b32 v80, v142, v90
	s_waitcnt lgkmcnt(3)
	v_pk_add_f32 v[92:93], v[84:85], v[92:93]
	v_cndmask_b32_e64 v89, v89, v83, s[42:43]
	s_waitcnt lgkmcnt(1)
	v_pk_add_f32 v[94:95], v[86:87], v[94:95]
	v_cndmask_b32_e64 v88, v88, v82, s[42:43]
	v_cndmask_b32_e64 v93, v93, v85, s[42:43]
	v_cndmask_b32_e64 v92, v92, v84, s[42:43]
	v_cndmask_b32_e64 v95, v95, v87, s[42:43]
	v_cndmask_b32_e64 v94, v94, v86, s[42:43]
	ds_bpermute_b32 v81, v142, v91
	ds_bpermute_b32 v82, v142, v88
	ds_bpermute_b32 v83, v142, v89
	ds_bpermute_b32 v84, v142, v92
	ds_bpermute_b32 v85, v142, v93
	ds_bpermute_b32 v86, v142, v94
	ds_bpermute_b32 v87, v142, v95
	ds_bpermute_b32 v108, v143, v99
	ds_bpermute_b32 v107, v143, v100
	ds_bpermute_b32 v109, v143, v102
	ds_bpermute_b32 v115, v143, v103
	s_waitcnt lgkmcnt(10)
	v_pk_add_f32 v[80:81], v[90:91], v[80:81]
	s_waitcnt lgkmcnt(8)
	v_pk_add_f32 v[82:83], v[88:89], v[82:83]
	s_waitcnt lgkmcnt(6)
	v_pk_add_f32 v[84:85], v[92:93], v[84:85]
	s_waitcnt lgkmcnt(4)
	v_pk_add_f32 v[86:87], v[94:95], v[86:87]
	s_and_saveexec_b64 s[0:1], s[2:3]
	s_cbranch_execz .LBB0_402
	ds_write_b128 v149, v[80:83]
	ds_write_b128 v149, v[84:87] offset:16
